# grid barrier: the XCD leader publishes the generation word before doing its own L1 invalidate (followers wake one invalidate earlier)
# baseline (speedup 1.0000x reference)
; __device__ __forceinline__ unsigned xb_ld(unsigned* p)              { return __hip_atomic_load(p, __ATOMIC_RELAXED, __HIP_MEMORY_SCOPE_AGENT); }
; __device__ __forceinline__ unsigned xb_add(unsigned* p, unsigned v) { return __hip_atomic_fetch_add(p, v, __ATOMIC_RELAXED, __HIP_MEMORY_SCOPE_AGENT); }
; #define XB_SPIN(cond, bar) do { unsigned _sp = 0; while (cond) { __builtin_amdgcn_s_sleep(1); \
;     if ((++_sp & 255u) == 0u) { if (xb_ld(&(bar)[XB_TMO])) break; if (_sp > XB_SPIN_CAP) { atomicAdd(&(bar)[XB_TMO], 1u); break; } } } } while (0)
; __device__ __forceinline__ void xcd_barrier(unsigned* bar, volatile LAS unsigned* st) {
;     ...
;             const unsigned og = xb_add(&bar[XB_TOP], 1u);
;             const unsigned tg = og / nx;
;             if (og + 1u == (tg + 1u) * nx) xb_add(&bar[XB_TOPGEN], 1u);
;             else XB_SPIN(xb_ld(&bar[XB_TOPGEN]) == tg, bar);
;             __builtin_amdgcn_fence(__ATOMIC_ACQUIRE, "agent");
;             xb_add(&bar[XB_XGEN(x)], 1u);
;             asm volatile("s_waitcnt vmcnt(0)" ::: "memory");
.LBB0_139:
	s_or_b64 exec, exec, s[4:5]
	s_mov_b64 s[4:5], exec
	v_mbcnt_lo_u32_b32 v0, s4, 0
	v_mbcnt_hi_u32_b32 v0, s5, v0
	v_cmp_eq_u32_e32 vcc, 0, v0
	s_waitcnt vmcnt(0)
	s_and_saveexec_b64 s[6:7], vcc
	s_cbranch_execz .LBB0_141
	s_bcnt1_i32_b64 s4, s[4:5]
	v_mov_b32_e32 v0, 0x2000
	v_mov_b32_e32 v1, s4
	global_atomic_add v0, v1, s[2:3] offset:1024
.LBB0_141:
	s_or_b64 exec, exec, s[6:7]
	buffer_inv sc1
	s_waitcnt vmcnt(0)
